# v23 plus 8 VALU slots per off-diagonal tile removed (self-max pair, two asm pads, four 0+x row-sum adds)
# baseline (speedup 1.0000x reference)
; __device__ __forceinline__ void attn_unit(const Params& P, int li, LAS unsigned char* lds, int b, int h, int qb, float lam, float one_m_li) {
;     ...
;             const bool diag = (t == cw);
;             if (diag) { p0 = f32x16{}; p1 = f32x16{}; }
;             else {
;                 const float nc0 = -(sl * ((float)((cw - t) * 64) + qinf) + m), nc1 = fadd_s(nc0, sl32);
;                 float b0[4], b1[4];
;                 b0[0] = nc0; b0[1] = fadd_s(nc0, sl8); b0[2] = fma2_s(sl8, nc0); b0[3] = fadd_s(nc0, sl24);
;                 b1[0] = nc1; b1[1] = fadd_s(nc1, sl8); b1[2] = fma2_s(sl8, nc1); b1[3] = fadd_s(nc1, sl24);
; #pragma unroll
;                 for (int q = 0; q < 4; ++q) {
;                     p0[4 * q] = b0[q]; p0[4 * q + 1] = fadd_s(b0[q], sl); p0[4 * q + 2] = fma2_s(sl, b0[q]); p0[4 * q + 3] = fadd_s(b0[q], sl3);
;                     p1[4 * q] = b1[q]; p1[4 * q + 1] = fadd_s(b1[q], sl); p1[4 * q + 2] = fma2_s(sl, b1[q]); p1[4 * q + 3] = fadd_s(b1[q], sl3);
;                 }
;             }
;             __builtin_amdgcn_sched_barrier(0);
;             __builtin_amdgcn_s_setprio(1);
; #pragma unroll
;             for (int d0 = 0; d0 < 4; ++d0) {
;                 p0 = __builtin_amdgcn_mfma_f32_32x32x16_bf16(kf[2 * d0], qr[d0], p0, 0, 0, 0);
;                 p1 = __builtin_amdgcn_mfma_f32_32x32x16_bf16(kf[2 * d0 + 1], qr[d0], p1, 0, 0, 0);
;             }
;             __builtin_amdgcn_s_setprio(0);
;             if (diag) {
;                 float qf = qinf; asm volatile("" : "+v"(qf));
; #pragma unroll
;                 for (int r = 0; r < 16; ++r) { const float d0 = qf - (float)crow(r, 0);
;                     p0[r] = fmaf(-sl, fabsf(d0), p0[r]); p1[r] = fmaf(-sl, fabsf(d0 - 32.f), p1[r]); }
;             }
;             float mx = max3f(p0[0], p1[0], p0[1]);
; #pragma unroll
;             for (int r = 1; r < 15; ++r) mx = max3f(mx, p1[r], p0[r + 1]);
;             mx = max3f(mx, p1[15], mx);
;             const float mt = xor32_max(mx);
;             bool resc; float ra;
;             if (diag) {
;                 resc = true; ra = ex2(m - mt); m = mt;
; #pragma unroll
;                 for (int r = 0; r < 16; ++r) { p0[r] -= mt; p1[r] -= mt; }
;                 const float X = qn * kmx - m + thr; const float ts = floorf(((float)(qpos - 63) - X / sl) * (1.f / 64.f));
.Lattn_offdiag:
	s_lshl_b32 s10, s21, 15
	s_and_b32 s22, s10, 0x18000
	v_add_u32_e32 v112, s22, v227
	v_add_u32_e32 v113, v112, v225
	ds_read_b128 v[76:79], v113
	ds_read_b128 v[68:71], v113 offset:4096
	v_add_u32_e32 v113, v112, v224
	ds_read_b128 v[72:75], v113
	ds_read_b128 v[92:95], v113 offset:4096
	v_add_u32_e32 v113, v112, v223
	v_add_u32_e32 v112, v112, v221
	ds_read_b128 v[64:67], v113
	ds_read_b128 v[84:87], v113 offset:4096
	ds_read_b128 v[88:91], v112
	ds_read_b128 v[80:83], v112 offset:4096
	s_sub_i32 s4, s31, s4
	s_lshl_b32 s4, s4, 6
	v_cvt_f32_i32_e32 v112, s4
	v_add_f32_e32 v112, v220, v112
	v_fma_f32 v112, v197, v112, v232
	v_xor_b32_e32 v96, 0x80000000, v112
	v_add_f32_e32 v112, v96, v201
	v_add_f32_e32 v100, v96, v199
	v_fma_f32 v104, v199, 2.0, v96
	v_add_f32_e32 v108, v96, v200
	v_add_f32_e32 v97, v96, v197
	v_fma_f32 v98, v197, 2.0, v96
	v_add_f32_e32 v116, v112, v199
	v_fma_f32 v120, v199, 2.0, v112
	v_add_f32_e32 v124, v112, v200
	v_add_f32_e32 v99, v96, v198
	v_add_f32_e32 v113, v112, v197
	v_fma_f32 v114, v197, 2.0, v112
	v_add_f32_e32 v115, v112, v198
	v_add_f32_e32 v101, v100, v197
	v_fma_f32 v102, v197, 2.0, v100
	v_add_f32_e32 v103, v100, v198
	v_add_f32_e32 v117, v116, v197
	v_fma_f32 v118, v197, 2.0, v116
	v_add_f32_e32 v119, v116, v198
	v_add_f32_e32 v105, v104, v197
	v_fma_f32 v106, v197, 2.0, v104
	v_add_f32_e32 v107, v104, v198
	v_add_f32_e32 v121, v120, v197
	v_fma_f32 v122, v197, 2.0, v120
	v_add_f32_e32 v123, v120, v198
	v_add_f32_e32 v109, v108, v197
	v_fma_f32 v110, v197, 2.0, v108
	v_add_f32_e32 v111, v108, v198
	v_add_f32_e32 v125, v124, v197
	v_fma_f32 v126, v197, 2.0, v124
	v_add_f32_e32 v127, v124, v198
	s_setprio 1
	s_waitcnt lgkmcnt(0)
	v_mfma_f32_32x32x16_bf16 v[96:111], v[76:79], v[128:131], v[96:111]
	v_mfma_f32_32x32x16_bf16 v[112:127], v[68:71], v[128:131], v[112:127]
	v_mfma_f32_32x32x16_bf16 v[96:111], v[72:75], v[132:135], v[96:111]
	v_mfma_f32_32x32x16_bf16 v[112:127], v[92:95], v[132:135], v[112:127]
	v_mfma_f32_32x32x16_bf16 v[96:111], v[64:67], v[136:139], v[96:111]
	v_mfma_f32_32x32x16_bf16 v[112:127], v[84:87], v[136:139], v[112:127]
	v_mfma_f32_32x32x16_bf16 v[96:111], v[88:91], v[140:143], v[96:111]
	v_mfma_f32_32x32x16_bf16 v[112:127], v[80:83], v[140:143], v[112:127]
	s_setprio 0
	s_nop 4
	v_max3_f32 v80, v96, v97, v98
	v_max3_f32 v80, v80, v99, v100
	v_max3_f32 v80, v80, v101, v102
	v_max3_f32 v80, v80, v103, v104
	v_max3_f32 v80, v80, v105, v106
	v_max3_f32 v80, v80, v107, v108
	v_max3_f32 v80, v80, v109, v110
	v_max3_f32 v80, v80, v111, v112
	v_max3_f32 v80, v80, v113, v114
	v_max3_f32 v80, v80, v115, v116
	v_max3_f32 v80, v80, v117, v118
	v_max3_f32 v80, v80, v119, v120
	v_max3_f32 v80, v80, v121, v122
	v_max3_f32 v80, v80, v123, v124
	v_max3_f32 v80, v80, v125, v126
	v_max3_f32 v80, v80, v127, v80
	s_nop 0
	v_mov_b32_e32 v81, v80
	s_nop 1
	v_permlane32_swap_b32_e32 v80, v81
	v_max_f32_e32 v233, v80, v81
	s_mov_b32 s4, 0x41000000
	v_cmp_lt_f32_e32 vcc, s4, v233
	s_mov_b64 s[22:23], 0
	s_cbranch_vccz .Lattn_od_keep
	v_max_f32_e32 v80, v233, v233
	v_max_f32_e32 v164, 0, v80
	v_exp_f32_e64 v192, -v164
	v_sub_f32_e32 v111, v111, v164
	v_sub_f32_e32 v110, v110, v164
	v_sub_f32_e32 v109, v109, v164
	v_sub_f32_e32 v108, v108, v164
	v_sub_f32_e32 v107, v107, v164
	v_sub_f32_e32 v106, v106, v164
	v_sub_f32_e32 v105, v105, v164
	v_sub_f32_e32 v104, v104, v164
	v_sub_f32_e32 v103, v103, v164
	v_sub_f32_e32 v102, v102, v164
	v_sub_f32_e32 v101, v101, v164
	v_sub_f32_e32 v100, v100, v164
	v_sub_f32_e32 v99, v99, v164
	v_sub_f32_e32 v98, v98, v164
	v_sub_f32_e32 v97, v97, v164
	v_sub_f32_e32 v96, v96, v164
	v_sub_f32_e32 v127, v127, v164
	v_sub_f32_e32 v126, v126, v164
	v_sub_f32_e32 v125, v125, v164
	v_sub_f32_e32 v124, v124, v164
	v_sub_f32_e32 v123, v123, v164
	v_sub_f32_e32 v122, v122, v164
	v_sub_f32_e32 v121, v121, v164
	v_sub_f32_e32 v120, v120, v164
	v_sub_f32_e32 v119, v119, v164
	v_sub_f32_e32 v118, v118, v164
	v_sub_f32_e32 v117, v117, v164
	v_sub_f32_e32 v116, v116, v164
	v_sub_f32_e32 v115, v115, v164
	v_sub_f32_e32 v114, v114, v164
	v_sub_f32_e32 v113, v113, v164
	v_sub_f32_e32 v112, v112, v164
	v_add_f32_e32 v187, v232, v164
	s_mov_b64 s[42:43], -1
	s_branch .LBB0_422

; #define LAS __attribute__((address_space(3)))
; #define AT_EXP(r_) do { p0[r_] = ex2(p0[r_]); p1[r_] = ex2(p1[r_]); lsa[(r_) & 1] = fadd_s(lsa[(r_) & 1], p0[r_]); lsb[(r_) & 1] = fadd_s(lsb[(r_) & 1], p1[r_]); } while (0)
; __device__ __forceinline__ void attn_unit(const Params& P, int li, LAS unsigned char* lds, int b, int h, int qb, float lam, float one_m_li) {
;     ...
;             if (havepf) {
;                 const LAS unsigned char* vp = lds + ((i + 3) & 3) * AT_STG + 16384 + r32 * 128;
;                 asm volatile("" : "+v"(p0), "+v"(p1));
;                 bf16x8 va[2][2];
; #pragma unroll
;                 for (int d = 0; d < 2; ++d) va[0][d] = *(const LAS bf16x8*)(vp + d * 4096 + coff[0]);
; #pragma unroll
;                 for (int g = 0; g < 8; ++g) {
;                     if (g + 1 < 8) {
; #pragma unroll
;                         for (int d = 0; d < 2; ++d) va[(g + 1) & 1][d] = *(const LAS bf16x8*)(vp + (((g + 1) & 1) * 2 + d) * 4096 + coff[((g + 1) >> 1) & 3]);
;                     }
; #pragma unroll
;                     for (int d = 0; d < 2; ++d) o[(g & 1) * 2 + d] = __builtin_amdgcn_mfma_f32_32x32x16_bf16(va[g & 1][d], pf[g >> 1], o[(g & 1) * 2 + d], 0, 0, 0);
;                     AT_EXP(2 * g); AT_EXP(2 * g + 1);
;                     __builtin_amdgcn_sched_barrier(0);
;                 }
;             } else {
; #pragma unroll
;                 for (int r = 0; r < 16; ++r) AT_EXP(r);
;             }
;             AT_PACK();
;             if (resc) { l *= ra;
; #pragma unroll
;                 for (int d = 0; d < 4; ++d) o[d] *= ra; }
;             l += (lsa[0] + lsa[1]) + (lsb[0] + lsb[1]);
.LBB0_436:
	s_add_i32 s10, s10, 0x18000
	s_and_b32 s4, s10, 0x18000
	v_add_u32_e32 v164, s4, v230
	v_add_u32_e32 v76, v164, v225
	ds_read_b128 v[64:67], v76 offset:16384
	ds_read_b128 v[72:75], v76 offset:20480
	v_exp_f32_e32 v68, v96
	v_exp_f32_e32 v69, v112
	s_waitcnt lgkmcnt(0)
	v_mfma_f32_32x32x16_bf16 v[48:63], v[64:67], v[156:159], v[48:63]
	ds_read_b128 v[64:67], v76 offset:24576
	ds_read_b128 v[76:79], v76 offset:28672
	v_exp_f32_e32 v70, v97
	v_exp_f32_e32 v71, v113
	v_mfma_f32_32x32x16_bf16 v[32:47], v[72:75], v[156:159], v[32:47]
	s_waitcnt lgkmcnt(0)
	v_mfma_f32_32x32x16_bf16 v[16:31], v[64:67], v[156:159], v[16:31]
	v_add_u32_e32 v92, v164, v224
	ds_read_b128 v[80:83], v92 offset:16384
	ds_read_b128 v[84:87], v92 offset:20480
	v_exp_f32_e32 v72, v98
	v_exp_f32_e32 v73, v114
	v_exp_f32_e32 v74, v99
	v_exp_f32_e32 v75, v115
	v_add_f32_e32 v93, v68, v72
	v_mfma_f32_32x32x16_bf16 v[0:15], v[76:79], v[156:159], v[0:15]
	v_add_f32_e32 v94, v69, v73
	v_add_f32_e32 v95, v70, v74
	v_add_f32_e32 v96, v71, v75
	s_waitcnt lgkmcnt(0)
	v_mfma_f32_32x32x16_bf16 v[48:63], v[80:83], v[152:155], v[48:63]
	ds_read_b128 v[64:67], v92 offset:24576
	ds_read_b128 v[88:91], v92 offset:28672
	v_exp_f32_e32 v76, v100
	v_exp_f32_e32 v77, v116
	v_exp_f32_e32 v78, v101
	v_exp_f32_e32 v79, v117
	v_add_f32_e32 v97, v93, v76
	v_add_f32_e32 v98, v94, v77
	v_mfma_f32_32x32x16_bf16 v[32:47], v[84:87], v[152:155], v[32:47]
	v_add_f32_e32 v99, v95, v78
	v_add_f32_e32 v96, v96, v79
	s_waitcnt lgkmcnt(0)
	v_mfma_f32_32x32x16_bf16 v[16:31], v[64:67], v[152:155], v[16:31]
	v_add_u32_e32 v100, v164, v223
	ds_read_b128 v[84:87], v100 offset:16384
	ds_read_b128 v[92:95], v100 offset:20480
	v_exp_f32_e32 v80, v102
	v_exp_f32_e32 v81, v118
	v_exp_f32_e32 v82, v103
	v_exp_f32_e32 v83, v119
	v_add_f32_e32 v101, v97, v80
	v_mfma_f32_32x32x16_bf16 v[0:15], v[88:91], v[152:155], v[0:15]
	v_add_f32_e32 v102, v98, v81
	v_add_f32_e32 v103, v99, v82
	v_add_f32_e32 v112, v96, v83
	s_waitcnt lgkmcnt(0)
	v_mfma_f32_32x32x16_bf16 v[48:63], v[84:87], v[148:151], v[48:63]
	ds_read_b128 v[64:67], v100 offset:24576
	ds_read_b128 v[96:99], v100 offset:28672
	v_exp_f32_e32 v84, v104
	v_exp_f32_e32 v85, v120
	v_exp_f32_e32 v86, v105
	v_exp_f32_e32 v87, v121
	v_add_f32_e32 v104, v101, v84
	v_add_f32_e32 v105, v102, v85
	v_mfma_f32_32x32x16_bf16 v[32:47], v[92:95], v[148:151], v[32:47]
	v_add_f32_e32 v113, v103, v86
	v_add_f32_e32 v112, v112, v87
	s_waitcnt lgkmcnt(0)
	v_mfma_f32_32x32x16_bf16 v[16:31], v[64:67], v[148:151], v[16:31]
	v_add_u32_e32 v114, v164, v221
	ds_read_b128 v[92:95], v114 offset:16384
	ds_read_b128 v[100:103], v114 offset:20480
	v_exp_f32_e32 v88, v106
	v_exp_f32_e32 v89, v122
	v_exp_f32_e32 v90, v107
	v_exp_f32_e32 v91, v123
	v_add_f32_e32 v104, v104, v88
	v_mfma_f32_32x32x16_bf16 v[0:15], v[96:99], v[148:151], v[0:15]
	v_add_f32_e32 v105, v105, v89
	v_add_f32_e32 v106, v113, v90
	v_add_f32_e32 v107, v112, v91
	s_waitcnt lgkmcnt(0)
	v_mfma_f32_32x32x16_bf16 v[48:63], v[92:95], v[144:147], v[48:63]
	ds_read_b128 v[64:67], v114 offset:24576
	ds_read_b128 v[96:99], v114 offset:28672
	v_exp_f32_e32 v92, v108
	v_exp_f32_e32 v93, v124
	v_exp_f32_e32 v94, v109
	v_exp_f32_e32 v95, v125
	v_add_f32_e32 v104, v104, v92
	v_add_f32_e32 v105, v105, v93
	v_mfma_f32_32x32x16_bf16 v[32:47], v[100:103], v[144:147], v[32:47]
	v_add_f32_e32 v106, v106, v94
	v_add_f32_e32 v107, v107, v95
	s_waitcnt lgkmcnt(0)
	v_mfma_f32_32x32x16_bf16 v[16:31], v[64:67], v[144:147], v[16:31]
	v_exp_f32_e32 v232, v110
	v_exp_f32_e32 v233, v126
	v_exp_f32_e32 v234, v111
	v_exp_f32_e32 v235, v127
	v_add_f32_e32 v64, v104, v232
	v_add_f32_e32 v65, v105, v233
	v_add_f32_e32 v66, v106, v234
	v_mfma_f32_32x32x16_bf16 v[0:15], v[96:99], v[144:147], v[0:15]
	v_add_f32_e32 v67, v107, v235
	s_andn2_b64 vcc, exec, s[42:43]
	s_cbranch_vccz .LBB0_425
	s_branch .LBB0_426
